# OUTA epilogue: progressive counted waits (vmcnt 12/9/11/14) for the first four row groups' residual loads instead of one vmcnt(0); on top of v80
# baseline (speedup 1.0000x reference)
; __device__ __forceinline__ float sum_x16(float v) { float a, b; swap16(v, a, b); return a + b; }
; __device__ __forceinline__ float sum_x32(float v) { float a, b; swap32(v, a, b); return a + b; }
;     __device__ __forceinline__ void operator()(const f32x4 (&acc)[2][2][4][2], const Unit& u, int wr, int wc, int fr, int fq, bool, PG8_LAS float*, PG8_LAS const float*) const {
;     ...
;         const size_t off0 = (size_t)(u.pm * BM + wr * 64 + fr) * 1024 + u.pn * BM + wc * 32 + 4 * fq;
;         const size_t offw = off0 + ((fq & 1) ? 12 : 0);
;     ...
;         EPO_LOAD(0); EPO_LOAD(1); EPO_LOAD(2); EPO_LOAD(3);
; #pragma unroll
;         for (int rg = 0; rg < 8; ++rg) {
;             const int ai = rg >> 2, m = rg & 3;
;             float ss = 0.f;
; #pragma unroll
;             for (int bj = 0; bj < 2; ++bj) {
;                 f32x4 p0, p1;
;                 if (FIRST) { p0 = pre[rg & 3][bj][0]; p1 = pre[rg & 3][bj][1]; }
;                 else { const u32x4 L = preh[rg & 3][bj]; const unsigned lx = L.x, ly = L.y, lz = L.z, lw = L.w; u32x2 X, Y; unsigned a0, b0, a1, b1; swap2(lx, lz, a0, b0); swap2(ly, lw, a1, b1);
;                        X.x = a0; X.y = a1; Y.x = b0; Y.y = b1; p0 = f16x4_to_f32(X); p1 = f16x4_to_f32(Y); }
;                 const f32x4 o0 = p0 + acc[ai][bj][m][0], o1 = p1 + acc[ai][bj][m][1];
;                 if (FIRST) {
;                     const unsigned x0 = cvt_pk_f16(o0[0], o0[1]), x1 = cvt_pk_f16(o0[2], o0[3]), y0 = cvt_pk_f16(o1[0], o1[1]), y1 = cvt_pk_f16(o1[2], o1[3]);
;                     unsigned a0, b0, a1, b1; swap2(x0, y0, a0, b0); swap2(x1, y1, a1, b1);
;                     u32x4 w; w.x = a0; w.y = a1; w.z = b0; w.w = b1;
;                     st16_wt(xh + offw + EPO_ROW(rg) + bj * HALF, w);
;                     ss += ((o0[0] * o0[0] + o0[1] * o0[1]) + (o0[2] * o0[2] + o0[3] * o0[3])) + ((o1[0] * o1[0] + o1[1] * o1[1]) + (o1[2] * o1[2] + o1[3] * o1[3]));
;                 } else {
;                     st16_wt(out + off0 + EPO_ROW(rg) + bj * HALF, __builtin_bit_cast(u32x4, o0));
;                     st16_wt(out + off0 + EPO_ROW(rg) + bj * HALF + 16, __builtin_bit_cast(u32x4, o1));
;                 }
;             }
;             if (rg + 4 < 8) EPO_LOAD(rg + 4);
;             if (FIRST) { ss = sum_x16(ss); ss = sum_x32(ss); ssq[rg] = ss; }
.LBB0_437:
	s_lshl_b32 s13, s20, 8
	s_add_i32 s13, s13, s40
	v_or_b32_e32 v128, s13, v181
	v_ashrrev_i32_e32 v129, 31, v128
	s_lshl_b32 s20, s51, 8
	v_lshlrev_b64 v[128:129], 10, v[128:129]
	s_ashr_i32 s21, s20, 31
	v_lshl_add_u64 v[192:193], v[128:129], 0, s[20:21]
	v_or_b32_e32 v192, v192, v180
	v_lshl_add_u64 v[194:195], v[192:193], 2, s[44:45]
	global_load_dwordx4 v[202:205], v[194:195], off
	global_load_dwordx4 v[206:209], v[194:195], off offset:64
	global_load_dwordx4 v[210:213], v[194:195], off offset:512
	global_load_dwordx4 v[214:217], v[194:195], off offset:576
	v_add_co_u32_e32 v128, vcc, s39, v194
	s_mov_b32 s2, 0x20000
	s_nop 0
	v_addc_co_u32_e32 v129, vcc, 0, v195, vcc
	global_load_dwordx4 v[172:175], v[128:129], off
	global_load_dwordx4 v[168:171], v[128:129], off offset:64
	global_load_dwordx4 v[164:167], v[128:129], off offset:512
	global_load_dwordx4 v[160:163], v[128:129], off offset:576
	v_add_co_u32_e32 v128, vcc, s2, v194
	s_mov_b32 s2, 0x30000
	s_nop 0
	v_addc_co_u32_e32 v129, vcc, 0, v195, vcc
	global_load_dwordx4 v[156:159], v[128:129], off
	global_load_dwordx4 v[152:155], v[128:129], off offset:64
	global_load_dwordx4 v[148:151], v[128:129], off offset:512
	global_load_dwordx4 v[144:147], v[128:129], off offset:576
	v_add_co_u32_e32 v128, vcc, s2, v194
	v_lshl_add_u64 v[192:193], v[192:193], 1, v[182:183]
	s_nop 0
	v_addc_co_u32_e32 v129, vcc, 0, v195, vcc
	global_load_dwordx4 v[140:143], v[128:129], off
	global_load_dwordx4 v[136:139], v[128:129], off offset:64
	global_load_dwordx4 v[132:135], v[128:129], off offset:512
	s_nop 0
	global_load_dwordx4 v[128:131], v[128:129], off offset:576
	s_mov_b32 s2, 0x80000
	s_waitcnt vmcnt(12)
	v_pk_add_f32 v[196:197], v[114:115], v[204:205]
	v_pk_add_f32 v[202:203], v[112:113], v[202:203]
	v_pk_add_f32 v[118:119], v[118:119], v[208:209]
	v_pk_add_f32 v[116:117], v[116:117], v[206:207]
	v_cvt_pk_f16_f32 v112, v202, v203
	v_cvt_pk_f16_f32 v113, v196, v197
	v_cvt_pk_f16_f32 v114, v116, v117
	v_cvt_pk_f16_f32 v115, v118, v119
	s_nop 0
	v_permlane16_swap_b32_e32 v112, v114
	v_permlane16_swap_b32_e32 v113, v115
	v_pk_add_f32 v[122:123], v[122:123], v[212:213]
	v_pk_add_f32 v[120:121], v[120:121], v[210:211]
	v_pk_add_f32 v[126:127], v[126:127], v[216:217]
	v_pk_add_f32 v[124:125], v[124:125], v[214:215]
	global_store_dwordx4 v[192:193], v[112:115], off
	s_waitcnt vmcnt(9)
	v_pk_add_f32 v[110:111], v[110:111], v[174:175]
	v_pk_add_f32 v[108:109], v[108:109], v[172:173]
	v_cvt_pk_f16_f32 v112, v120, v121
	v_cvt_pk_f16_f32 v113, v122, v123
	v_cvt_pk_f16_f32 v114, v124, v125
	v_cvt_pk_f16_f32 v115, v126, v127
	s_nop 0
	v_permlane16_swap_b32_e32 v112, v114
	v_permlane16_swap_b32_e32 v113, v115
	global_store_dwordx4 v[192:193], v[112:115], off offset:256
	v_pk_add_f32 v[170:171], v[106:107], v[170:171]
	v_pk_add_f32 v[168:169], v[104:105], v[168:169]
	v_mov_b32_e32 v113, v120
	v_mov_b32_e32 v120, v203
	v_mov_b32_e32 v112, v202
	v_pk_mul_f32 v[114:115], v[120:121], v[120:121]
	v_cvt_pk_f16_f32 v104, v108, v109
	v_pk_fma_f32 v[112:113], v[112:113], v[112:113], v[114:115]
	v_mov_b32_e32 v115, v122
	v_mov_b32_e32 v122, v197
	v_mov_b32_e32 v114, v196
	v_pk_mul_f32 v[120:121], v[122:123], v[122:123]
	v_cvt_pk_f16_f32 v105, v110, v111
	v_pk_fma_f32 v[114:115], v[114:115], v[114:115], v[120:121]
	v_cvt_pk_f16_f32 v106, v168, v169
	v_pk_add_f32 v[112:113], v[112:113], v[114:115]
	v_mov_b32_e32 v115, v124
	v_mov_b32_e32 v124, v117
	v_mov_b32_e32 v114, v116
	v_pk_mul_f32 v[116:117], v[124:125], v[124:125]
	v_cvt_pk_f16_f32 v107, v170, v171
	v_pk_fma_f32 v[114:115], v[114:115], v[114:115], v[116:117]
	v_mov_b32_e32 v117, v126
	v_mov_b32_e32 v126, v119
	v_mov_b32_e32 v116, v118
	v_pk_mul_f32 v[118:119], v[126:127], v[126:127]
	v_permlane16_swap_b32_e32 v104, v106
	v_pk_fma_f32 v[116:117], v[116:117], v[116:117], v[118:119]
	v_permlane16_swap_b32_e32 v105, v107
	v_pk_add_f32 v[114:115], v[114:115], v[116:117]
	v_pk_add_f32 v[102:103], v[102:103], v[166:167]
	v_pk_add_f32 v[112:113], v[112:113], v[114:115]
	v_pk_add_f32 v[100:101], v[100:101], v[164:165]
	v_pk_add_f32 v[196:197], v[112:113], v[112:113] op_sel:[0,1] op_sel_hi:[1,0]
	v_add_co_u32_e32 v112, vcc, s2, v194
	s_mov_b32 s2, 0x8000
	s_nop 0
	v_addc_co_u32_e32 v113, vcc, 0, v195, vcc
	v_add_co_u32_e32 v172, vcc, s2, v192
	global_load_dwordx4 v[124:127], v[112:113], off
	global_load_dwordx4 v[120:123], v[112:113], off offset:64
	global_load_dwordx4 v[116:119], v[112:113], off offset:512
	s_nop 0
	global_load_dwordx4 v[112:115], v[112:113], off offset:576
	v_addc_co_u32_e32 v173, vcc, 0, v193, vcc
	global_store_dwordx4 v[172:173], v[104:107], off
	s_mov_b32 s2, 0x90000
	s_waitcnt vmcnt(11)
; __device__ __forceinline__ void st16_wt(void* p, u32x4 v) { if (WT_STORES) asm volatile("global_store_dwordx4 %0, %1, off sc1\n\ts_nop 1" :: "v"(p), "v"(v) : "memory"); else *(u32x4*)p = v; }
; __device__ __forceinline__ unsigned cvt_pk_f16(float lo, float hi) { const f32x2_t v = {lo, hi}; const f16x2_t h = __builtin_convertvector(v, f16x2_t); return __builtin_bit_cast(unsigned, h); }
;     __device__ __forceinline__ void operator()(const f32x4 (&acc)[2][2][4][2], const Unit& u, int wr, int wc, int fr, int fq, bool, PG8_LAS float*, PG8_LAS const float*) const {
;     ...
;         for (int rg = 0; rg < 8; ++rg) {
;             const int ai = rg >> 2, m = rg & 3;
;             float ss = 0.f;
; #pragma unroll
;             for (int bj = 0; bj < 2; ++bj) {
;                 f32x4 p0, p1;
;                 if (FIRST) { p0 = pre[rg & 3][bj][0]; p1 = pre[rg & 3][bj][1]; }
;                 else { const u32x4 L = preh[rg & 3][bj]; const unsigned lx = L.x, ly = L.y, lz = L.z, lw = L.w; u32x2 X, Y; unsigned a0, b0, a1, b1; swap2(lx, lz, a0, b0); swap2(ly, lw, a1, b1);
;                        X.x = a0; X.y = a1; Y.x = b0; Y.y = b1; p0 = f16x4_to_f32(X); p1 = f16x4_to_f32(Y); }
;                 const f32x4 o0 = p0 + acc[ai][bj][m][0], o1 = p1 + acc[ai][bj][m][1];
;                 if (FIRST) {
;                     const unsigned x0 = cvt_pk_f16(o0[0], o0[1]), x1 = cvt_pk_f16(o0[2], o0[3]), y0 = cvt_pk_f16(o1[0], o1[1]), y1 = cvt_pk_f16(o1[2], o1[3]);
;                     unsigned a0, b0, a1, b1; swap2(x0, y0, a0, b0); swap2(x1, y1, a1, b1);
;                     u32x4 w; w.x = a0; w.y = a1; w.z = b0; w.w = b1;
;                     st16_wt(xh + offw + EPO_ROW(rg) + bj * HALF, w);
;                     ss += ((o0[0] * o0[0] + o0[1] * o0[1]) + (o0[2] * o0[2] + o0[3] * o0[3])) + ((o1[0] * o1[0] + o1[1] * o1[1]) + (o1[2] * o1[2] + o1[3] * o1[3]));
;                 } else {
;                     st16_wt(out + off0 + EPO_ROW(rg) + bj * HALF, __builtin_bit_cast(u32x4, o0));
;                     st16_wt(out + off0 + EPO_ROW(rg) + bj * HALF + 16, __builtin_bit_cast(u32x4, o1));
;                 }
;             }
;             if (rg + 4 < 8) EPO_LOAD(rg + 4);
	v_pk_add_f32 v[94:95], v[94:95], v[158:159]
	v_mul_f32_e32 v104, v109, v109
	v_mul_f32_e32 v105, v111, v111
	v_fmac_f32_e32 v104, v108, v108
	v_fmac_f32_e32 v105, v110, v110
	v_add_f32_e32 v104, v104, v105
	v_mul_f32_e32 v105, v169, v169
	v_mul_f32_e32 v106, v171, v171
	v_fmac_f32_e32 v105, v168, v168
	v_fmac_f32_e32 v106, v170, v170
	v_add_f32_e32 v105, v105, v106
	v_add_f32_e32 v108, v104, v105
	v_pk_add_f32 v[104:105], v[98:99], v[162:163]
	v_pk_add_f32 v[106:107], v[96:97], v[160:161]
	v_cvt_pk_f16_f32 v96, v100, v101
	v_cvt_pk_f16_f32 v97, v102, v103
	v_cvt_pk_f16_f32 v98, v106, v107
	v_cvt_pk_f16_f32 v99, v104, v105
	s_nop 0
	v_permlane16_swap_b32_e32 v96, v98
	v_permlane16_swap_b32_e32 v97, v99
	global_store_dwordx4 v[172:173], v[96:99], off offset:256
	v_pk_add_f32 v[92:93], v[92:93], v[156:157]
	v_pk_add_f32 v[154:155], v[90:91], v[154:155]
	v_mul_f32_e32 v96, v101, v101
	v_mul_f32_e32 v97, v103, v103
	v_fmac_f32_e32 v96, v100, v100
	v_fmac_f32_e32 v97, v102, v102
	v_add_f32_e32 v96, v96, v97
	v_mul_f32_e32 v97, v107, v107
	v_mul_f32_e32 v98, v105, v105
	v_fmac_f32_e32 v97, v106, v106
	v_fmac_f32_e32 v98, v104, v104
	v_add_f32_e32 v97, v97, v98
	v_add_f32_e32 v96, v96, v97
	v_add_f32_e32 v160, v108, v96
	v_add_co_u32_e32 v96, vcc, s2, v194
	v_pk_add_f32 v[152:153], v[88:89], v[152:153]
	s_nop 0
	v_addc_co_u32_e32 v97, vcc, 0, v195, vcc
	v_cvt_pk_f16_f32 v88, v92, v93
	v_cvt_pk_f16_f32 v89, v94, v95
	v_cvt_pk_f16_f32 v90, v152, v153
	v_cvt_pk_f16_f32 v91, v154, v155
	v_add_co_u32_e32 v156, vcc, s39, v192
	v_permlane16_swap_b32_e32 v88, v90
	v_permlane16_swap_b32_e32 v89, v91
	v_addc_co_u32_e32 v157, vcc, 0, v193, vcc
	global_load_dwordx4 v[108:111], v[96:97], off
	global_load_dwordx4 v[104:107], v[96:97], off offset:64
	global_load_dwordx4 v[100:103], v[96:97], off offset:512
	s_nop 0
	global_load_dwordx4 v[96:99], v[96:97], off offset:576
	v_pk_add_f32 v[86:87], v[86:87], v[150:151]
	global_store_dwordx4 v[156:157], v[88:91], off
	v_pk_add_f32 v[84:85], v[84:85], v[148:149]
	s_mov_b32 s2, 0xa0000
	v_mul_f32_e32 v88, v93, v93
	v_mul_f32_e32 v89, v95, v95
	v_fmac_f32_e32 v88, v92, v92
	v_fmac_f32_e32 v89, v94, v94
	v_add_f32_e32 v88, v88, v89
	v_mul_f32_e32 v89, v153, v153
	v_mul_f32_e32 v90, v155, v155
	v_fmac_f32_e32 v89, v152, v152
	v_fmac_f32_e32 v90, v154, v154
	v_add_f32_e32 v89, v89, v90
	v_add_f32_e32 v92, v88, v89
	v_pk_add_f32 v[88:89], v[82:83], v[146:147]
	v_pk_add_f32 v[90:91], v[80:81], v[144:145]
	v_cvt_pk_f16_f32 v80, v84, v85
	v_cvt_pk_f16_f32 v81, v86, v87
	v_cvt_pk_f16_f32 v82, v90, v91
	v_cvt_pk_f16_f32 v83, v88, v89
	s_nop 0
	v_permlane16_swap_b32_e32 v80, v82
	v_permlane16_swap_b32_e32 v81, v83
	global_store_dwordx4 v[156:157], v[80:83], off offset:256
	s_waitcnt vmcnt(14)
	v_pk_add_f32 v[78:79], v[78:79], v[142:143]
	v_pk_add_f32 v[76:77], v[76:77], v[140:141]
	v_mul_f32_e32 v80, v85, v85
	v_mul_f32_e32 v81, v87, v87
	v_fmac_f32_e32 v80, v84, v84
	v_fmac_f32_e32 v81, v86, v86
	v_add_f32_e32 v80, v80, v81
	v_mul_f32_e32 v81, v91, v91
	v_mul_f32_e32 v82, v89, v89
	v_fmac_f32_e32 v81, v90, v90
	v_fmac_f32_e32 v82, v88, v88
	v_add_f32_e32 v81, v81, v82
	v_add_f32_e32 v80, v80, v81
	v_add_f32_e32 v144, v92, v80
	v_add_co_u32_e32 v80, vcc, s2, v194
	v_pk_add_f32 v[138:139], v[74:75], v[138:139]
	s_nop 0
	v_addc_co_u32_e32 v81, vcc, 0, v195, vcc
	v_pk_add_f32 v[136:137], v[72:73], v[136:137]
	s_mov_b32 s2, 0x18000
	v_cvt_pk_f16_f32 v72, v76, v77
	v_cvt_pk_f16_f32 v73, v78, v79
	v_cvt_pk_f16_f32 v74, v136, v137
	v_cvt_pk_f16_f32 v75, v138, v139
	v_add_co_u32_e32 v140, vcc, s2, v192
	v_permlane16_swap_b32_e32 v72, v74
	v_permlane16_swap_b32_e32 v73, v75
	v_addc_co_u32_e32 v141, vcc, 0, v193, vcc
	global_load_dwordx4 v[92:95], v[80:81], off
	global_load_dwordx4 v[88:91], v[80:81], off offset:64
	global_load_dwordx4 v[84:87], v[80:81], off offset:512
	s_nop 0
	global_load_dwordx4 v[80:83], v[80:81], off offset:576
	v_pk_add_f32 v[70:71], v[70:71], v[134:135]
	global_store_dwordx4 v[140:141], v[72:75], off
	v_pk_add_f32 v[68:69], v[68:69], v[132:133]
	s_mov_b32 s2, 0xb0000
	v_mul_f32_e32 v72, v77, v77
	v_mul_f32_e32 v73, v79, v79
	v_fmac_f32_e32 v72, v76, v76
	v_fmac_f32_e32 v73, v78, v78
	v_add_f32_e32 v72, v72, v73
	v_mul_f32_e32 v73, v137, v137
	v_mul_f32_e32 v74, v139, v139
	v_fmac_f32_e32 v73, v136, v136
	v_fmac_f32_e32 v74, v138, v138
	v_add_f32_e32 v73, v73, v74
	v_add_f32_e32 v76, v72, v73
	v_pk_add_f32 v[72:73], v[66:67], v[130:131]
	v_pk_add_f32 v[74:75], v[64:65], v[128:129]
	v_cvt_pk_f16_f32 v64, v68, v69
	v_cvt_pk_f16_f32 v65, v70, v71
	v_cvt_pk_f16_f32 v66, v74, v75
	v_cvt_pk_f16_f32 v67, v72, v73
	s_nop 0
	v_permlane16_swap_b32_e32 v64, v66
	v_permlane16_swap_b32_e32 v65, v67
	global_store_dwordx4 v[140:141], v[64:67], off offset:256
	s_waitcnt vmcnt(17)
	v_pk_add_f32 v[62:63], v[62:63], v[126:127]
	v_pk_add_f32 v[60:61], v[60:61], v[124:125]
	v_mul_f32_e32 v64, v69, v69
	v_mul_f32_e32 v65, v71, v71
	v_fmac_f32_e32 v64, v68, v68
	v_fmac_f32_e32 v65, v70, v70
	v_add_f32_e32 v64, v64, v65
	v_mul_f32_e32 v65, v75, v75
	v_mul_f32_e32 v66, v73, v73
	v_fmac_f32_e32 v65, v74, v74
	v_fmac_f32_e32 v66, v72, v72
	v_add_f32_e32 v65, v65, v66
	v_add_f32_e32 v64, v64, v65
	v_add_f32_e32 v128, v76, v64
	v_add_co_u32_e32 v64, vcc, s2, v194
	s_waitcnt vmcnt(16)
; __device__ __forceinline__ void st16_wt(void* p, u32x4 v) { if (WT_STORES) asm volatile("global_store_dwordx4 %0, %1, off sc1\n\ts_nop 1" :: "v"(p), "v"(v) : "memory"); else *(u32x4*)p = v; }
; __device__ __forceinline__ unsigned cvt_pk_f16(float lo, float hi) { const f32x2_t v = {lo, hi}; const f16x2_t h = __builtin_convertvector(v, f16x2_t); return __builtin_bit_cast(unsigned, h); }
;     __device__ __forceinline__ void operator()(const f32x4 (&acc)[2][2][4][2], const Unit& u, int wr, int wc, int fr, int fq, bool, PG8_LAS float*, PG8_LAS const float*) const {
;     ...
;         for (int rg = 0; rg < 8; ++rg) {
;             const int ai = rg >> 2, m = rg & 3;
;             float ss = 0.f;
; #pragma unroll
;             for (int bj = 0; bj < 2; ++bj) {
;                 f32x4 p0, p1;
;                 if (FIRST) { p0 = pre[rg & 3][bj][0]; p1 = pre[rg & 3][bj][1]; }
;                 else { const u32x4 L = preh[rg & 3][bj]; const unsigned lx = L.x, ly = L.y, lz = L.z, lw = L.w; u32x2 X, Y; unsigned a0, b0, a1, b1; swap2(lx, lz, a0, b0); swap2(ly, lw, a1, b1);
;                        X.x = a0; X.y = a1; Y.x = b0; Y.y = b1; p0 = f16x4_to_f32(X); p1 = f16x4_to_f32(Y); }
;                 const f32x4 o0 = p0 + acc[ai][bj][m][0], o1 = p1 + acc[ai][bj][m][1];
;                 if (FIRST) {
;                     const unsigned x0 = cvt_pk_f16(o0[0], o0[1]), x1 = cvt_pk_f16(o0[2], o0[3]), y0 = cvt_pk_f16(o1[0], o1[1]), y1 = cvt_pk_f16(o1[2], o1[3]);
;                     unsigned a0, b0, a1, b1; swap2(x0, y0, a0, b0); swap2(x1, y1, a1, b1);
;                     u32x4 w; w.x = a0; w.y = a1; w.z = b0; w.w = b1;
;                     st16_wt(xh + offw + EPO_ROW(rg) + bj * HALF, w);
;                     ss += ((o0[0] * o0[0] + o0[1] * o0[1]) + (o0[2] * o0[2] + o0[3] * o0[3])) + ((o1[0] * o1[0] + o1[1] * o1[1]) + (o1[2] * o1[2] + o1[3] * o1[3]));
;                 } else {
;                     st16_wt(out + off0 + EPO_ROW(rg) + bj * HALF, __builtin_bit_cast(u32x4, o0));
;                     st16_wt(out + off0 + EPO_ROW(rg) + bj * HALF + 16, __builtin_bit_cast(u32x4, o1));
;                 }
;             }
;             if (rg + 4 < 8) EPO_LOAD(rg + 4);
	v_pk_add_f32 v[122:123], v[54:55], v[122:123]
	v_addc_co_u32_e32 v65, vcc, 0, v195, vcc
	global_load_dwordx4 v[76:79], v[64:65], off
	global_load_dwordx4 v[72:75], v[64:65], off offset:64
	global_load_dwordx4 v[68:71], v[64:65], off offset:512
	s_nop 0
	global_load_dwordx4 v[64:67], v[64:65], off offset:576
	v_pk_add_f32 v[120:121], v[52:53], v[120:121]
	s_mov_b32 s2, 0x40000
	v_cvt_pk_f16_f32 v52, v60, v61
	v_cvt_pk_f16_f32 v53, v62, v63
	v_cvt_pk_f16_f32 v54, v120, v121
	v_cvt_pk_f16_f32 v55, v122, v123
	v_add_co_u32_e32 v124, vcc, s2, v192
	v_permlane16_swap_b32_e32 v52, v54
	v_permlane16_swap_b32_e32 v53, v55
	v_addc_co_u32_e32 v125, vcc, 0, v193, vcc
	global_store_dwordx4 v[124:125], v[52:55], off
	s_waitcnt vmcnt(16)
	v_pk_add_f32 v[46:47], v[46:47], v[110:111]
	v_pk_add_f32 v[44:45], v[44:45], v[108:109]
	v_pk_add_f32 v[52:53], v[58:59], v[118:119]
	v_pk_add_f32 v[54:55], v[56:57], v[116:117]
	v_pk_add_f32 v[56:57], v[50:51], v[114:115]
	v_pk_add_f32 v[58:59], v[48:49], v[112:113]
	v_cvt_pk_f16_f32 v48, v54, v55
	v_cvt_pk_f16_f32 v49, v52, v53
	v_cvt_pk_f16_f32 v50, v58, v59
	v_cvt_pk_f16_f32 v51, v56, v57
	s_nop 0
	v_permlane16_swap_b32_e32 v48, v50
	v_permlane16_swap_b32_e32 v49, v51
	global_store_dwordx4 v[124:125], v[48:51], off offset:256
	s_mov_b32 s2, 0x48000
	s_waitcnt vmcnt(11)
	v_pk_add_f32 v[30:31], v[30:31], v[94:95]
	v_mul_f32_e32 v48, v61, v61
	v_mul_f32_e32 v49, v63, v63
	v_fmac_f32_e32 v48, v60, v60
	v_fmac_f32_e32 v49, v62, v62
	v_add_f32_e32 v48, v48, v49
	v_mul_f32_e32 v49, v121, v121
	v_mul_f32_e32 v50, v123, v123
	v_fmac_f32_e32 v49, v120, v120
	v_fmac_f32_e32 v50, v122, v122
	v_add_f32_e32 v49, v49, v50
	v_add_f32_e32 v48, v48, v49
	v_mul_f32_e32 v49, v55, v55
	v_mul_f32_e32 v50, v53, v53
	v_fmac_f32_e32 v49, v54, v54
	v_fmac_f32_e32 v50, v52, v52
	v_add_f32_e32 v49, v49, v50
	v_mul_f32_e32 v50, v59, v59
	v_mul_f32_e32 v51, v57, v57
	v_fmac_f32_e32 v50, v58, v58
	v_fmac_f32_e32 v51, v56, v56
	v_add_f32_e32 v50, v50, v51
	v_add_f32_e32 v49, v49, v50
	v_pk_add_f32 v[50:51], v[38:39], v[106:107]
	v_pk_add_f32 v[52:53], v[36:37], v[104:105]
	v_cvt_pk_f16_f32 v36, v44, v45
	v_cvt_pk_f16_f32 v37, v46, v47
	v_cvt_pk_f16_f32 v38, v52, v53
	v_cvt_pk_f16_f32 v39, v50, v51
	v_add_co_u32_e32 v54, vcc, s2, v192
	v_permlane16_swap_b32_e32 v36, v38
	v_permlane16_swap_b32_e32 v37, v39
	v_addc_co_u32_e32 v55, vcc, 0, v193, vcc
	global_store_dwordx4 v[54:55], v[36:39], off
	v_pk_add_f32 v[28:29], v[28:29], v[92:93]
	s_mov_b32 s2, 0x50000
	v_pk_add_f32 v[36:37], v[42:43], v[102:103]
	v_pk_add_f32 v[38:39], v[40:41], v[100:101]
	v_pk_add_f32 v[40:41], v[34:35], v[98:99]
	v_pk_add_f32 v[42:43], v[32:33], v[96:97]
	v_cvt_pk_f16_f32 v32, v38, v39
	v_cvt_pk_f16_f32 v33, v36, v37
	v_cvt_pk_f16_f32 v34, v42, v43
	v_cvt_pk_f16_f32 v35, v40, v41
	s_nop 0
	v_permlane16_swap_b32_e32 v32, v34
	v_permlane16_swap_b32_e32 v33, v35
	global_store_dwordx4 v[54:55], v[32:35], off offset:256
	s_waitcnt vmcnt(7)
	v_pk_add_f32 v[10:11], v[10:11], v[78:79]
	v_pk_add_f32 v[8:9], v[8:9], v[76:77]
	v_mul_f32_e32 v32, v45, v45
	v_mul_f32_e32 v33, v47, v47
	v_fmac_f32_e32 v32, v44, v44
	v_fmac_f32_e32 v33, v46, v46
	v_add_f32_e32 v32, v32, v33
	v_mul_f32_e32 v33, v53, v53
	v_mul_f32_e32 v34, v51, v51
	v_fmac_f32_e32 v33, v52, v52
	v_fmac_f32_e32 v34, v50, v50
	v_add_f32_e32 v33, v33, v34
	v_add_f32_e32 v32, v32, v33
	v_mul_f32_e32 v33, v39, v39
	v_mul_f32_e32 v34, v37, v37
	v_fmac_f32_e32 v33, v38, v38
	v_fmac_f32_e32 v34, v36, v36
	v_add_f32_e32 v33, v33, v34
	v_mul_f32_e32 v34, v43, v43
	v_mul_f32_e32 v35, v41, v41
	v_fmac_f32_e32 v34, v42, v42
	v_fmac_f32_e32 v35, v40, v40
	v_add_f32_e32 v34, v34, v35
	v_add_f32_e32 v33, v33, v34
	v_pk_add_f32 v[34:35], v[22:23], v[90:91]
	v_pk_add_f32 v[36:37], v[20:21], v[88:89]
	v_cvt_pk_f16_f32 v20, v28, v29
	v_cvt_pk_f16_f32 v21, v30, v31
	v_cvt_pk_f16_f32 v22, v36, v37
	v_cvt_pk_f16_f32 v23, v34, v35
	v_add_co_u32_e32 v38, vcc, s2, v192
	v_permlane16_swap_b32_e32 v20, v22
	v_permlane16_swap_b32_e32 v21, v23
	v_addc_co_u32_e32 v39, vcc, 0, v193, vcc
	global_store_dwordx4 v[38:39], v[20:23], off
	s_mov_b32 s2, 0x58000
	s_waitcnt vmcnt(6)
; __device__ __forceinline__ float sum_x16(float v) { float a, b; swap16(v, a, b); return a + b; }
; __device__ __forceinline__ float sum_x32(float v) { float a, b; swap32(v, a, b); return a + b; }
; __device__ __forceinline__ void st16_wt(void* p, u32x4 v) { if (WT_STORES) asm volatile("global_store_dwordx4 %0, %1, off sc1\n\ts_nop 1" :: "v"(p), "v"(v) : "memory"); else *(u32x4*)p = v; }
; __device__ __forceinline__ unsigned cvt_pk_f16(float lo, float hi) { const f32x2_t v = {lo, hi}; const f16x2_t h = __builtin_convertvector(v, f16x2_t); return __builtin_bit_cast(unsigned, h); }
;     __device__ __forceinline__ void operator()(const f32x4 (&acc)[2][2][4][2], const Unit& u, int wr, int wc, int fr, int fq, bool, PG8_LAS float*, PG8_LAS const float*) const {
;     ...
;                 const f32x4 o0 = p0 + acc[ai][bj][m][0], o1 = p1 + acc[ai][bj][m][1];
;                 if (FIRST) {
;                     const unsigned x0 = cvt_pk_f16(o0[0], o0[1]), x1 = cvt_pk_f16(o0[2], o0[3]), y0 = cvt_pk_f16(o1[0], o1[1]), y1 = cvt_pk_f16(o1[2], o1[3]);
;                     unsigned a0, b0, a1, b1; swap2(x0, y0, a0, b0); swap2(x1, y1, a1, b1);
;                     u32x4 w; w.x = a0; w.y = a1; w.z = b0; w.w = b1;
;                     st16_wt(xh + offw + EPO_ROW(rg) + bj * HALF, w);
;                     ss += ((o0[0] * o0[0] + o0[1] * o0[1]) + (o0[2] * o0[2] + o0[3] * o0[3])) + ((o1[0] * o1[0] + o1[1] * o1[1]) + (o1[2] * o1[2] + o1[3] * o1[3]));
;                 } else {
;                     st16_wt(out + off0 + EPO_ROW(rg) + bj * HALF, __builtin_bit_cast(u32x4, o0));
;                     st16_wt(out + off0 + EPO_ROW(rg) + bj * HALF + 16, __builtin_bit_cast(u32x4, o1));
;                 }
;             }
;             if (rg + 4 < 8) EPO_LOAD(rg + 4);
;             if (FIRST) { ss = sum_x16(ss); ss = sum_x32(ss); ssq[rg] = ss; }
;         }
;         if (FIRST) {
; #pragma unroll
;             for (int hh = 0; hh < 2; ++hh) {
;                 const float v = (fq == 0) ? ssq[4 * hh] : (fq == 1) ? ssq[4 * hh + 1] : (fq == 2) ? ssq[4 * hh + 2] : ssq[4 * hh + 3];
;                 const int r = u.pm * BM + hh * HALF + wr * 64 + fq * 16 + fr;
;                 part[(size_t)r * 16 + u.pn * 4 + wc] = v;
	v_pk_add_f32 v[6:7], v[6:7], v[70:71]
	v_pk_add_f32 v[20:21], v[26:27], v[86:87]
	v_pk_add_f32 v[22:23], v[24:25], v[84:85]
	v_pk_add_f32 v[24:25], v[18:19], v[82:83]
	v_pk_add_f32 v[26:27], v[16:17], v[80:81]
	v_cvt_pk_f16_f32 v16, v22, v23
	v_cvt_pk_f16_f32 v17, v20, v21
	v_cvt_pk_f16_f32 v18, v26, v27
	v_cvt_pk_f16_f32 v19, v24, v25
	s_nop 0
	v_permlane16_swap_b32_e32 v16, v18
	v_permlane16_swap_b32_e32 v17, v19
	global_store_dwordx4 v[38:39], v[16:19], off offset:256
	v_pk_add_f32 v[4:5], v[4:5], v[68:69]
	s_waitcnt vmcnt(6)
	v_pk_add_f32 v[14:15], v[14:15], v[66:67]
	v_mul_f32_e32 v16, v29, v29
	v_mul_f32_e32 v17, v31, v31
	v_fmac_f32_e32 v16, v28, v28
	v_fmac_f32_e32 v17, v30, v30
	v_add_f32_e32 v16, v16, v17
	v_mul_f32_e32 v17, v37, v37
	v_mul_f32_e32 v18, v35, v35
	v_fmac_f32_e32 v17, v36, v36
	v_fmac_f32_e32 v18, v34, v34
	v_add_f32_e32 v17, v17, v18
	v_add_f32_e32 v16, v16, v17
	v_mul_f32_e32 v17, v23, v23
	v_mul_f32_e32 v18, v21, v21
	v_fmac_f32_e32 v17, v22, v22
	v_fmac_f32_e32 v18, v20, v20
	v_add_f32_e32 v17, v17, v18
	v_mul_f32_e32 v18, v27, v27
	v_mul_f32_e32 v19, v25, v25
	v_fmac_f32_e32 v18, v26, v26
	v_fmac_f32_e32 v19, v24, v24
	v_add_f32_e32 v18, v18, v19
	v_add_f32_e32 v17, v17, v18
	v_pk_add_f32 v[18:19], v[2:3], v[74:75]
	v_pk_add_f32 v[20:21], v[0:1], v[72:73]
	v_cvt_pk_f16_f32 v0, v8, v9
	v_cvt_pk_f16_f32 v1, v10, v11
	v_cvt_pk_f16_f32 v2, v20, v21
	v_cvt_pk_f16_f32 v3, v18, v19
	v_add_co_u32_e32 v22, vcc, s2, v192
	v_permlane16_swap_b32_e32 v0, v2
	v_permlane16_swap_b32_e32 v1, v3
	v_addc_co_u32_e32 v23, vcc, 0, v193, vcc
	v_pk_add_f32 v[12:13], v[12:13], v[64:65]
	global_store_dwordx4 v[22:23], v[0:3], off
	v_add_f32_e32 v48, v48, v49
	v_add_f32_e32 v32, v32, v33
	v_cvt_pk_f16_f32 v0, v4, v5
	v_cvt_pk_f16_f32 v1, v6, v7
	v_cvt_pk_f16_f32 v2, v12, v13
	v_cvt_pk_f16_f32 v3, v14, v15
	s_nop 0
	v_permlane16_swap_b32_e32 v0, v2
	v_permlane16_swap_b32_e32 v1, v3
	global_store_dwordx4 v[22:23], v[0:3], off offset:256
	v_add_f32_e32 v16, v16, v17
	v_mov_b32_e32 v197, v196
	v_mul_f32_e32 v0, v9, v9
	v_mul_f32_e32 v1, v11, v11
	v_fmac_f32_e32 v0, v8, v8
	v_fmac_f32_e32 v1, v10, v10
	v_add_f32_e32 v0, v0, v1
	v_mul_f32_e32 v1, v21, v21
	v_mul_f32_e32 v2, v19, v19
	v_fmac_f32_e32 v1, v20, v20
	v_fmac_f32_e32 v2, v18, v18
	v_add_f32_e32 v1, v1, v2
	v_add_f32_e32 v0, v0, v1
	v_mul_f32_e32 v1, v5, v5
	v_mul_f32_e32 v2, v7, v7
	v_fmac_f32_e32 v1, v4, v4
	v_fmac_f32_e32 v2, v6, v6
	v_add_f32_e32 v1, v1, v2
	v_mul_f32_e32 v2, v13, v13
	v_mul_f32_e32 v3, v15, v15
	v_fmac_f32_e32 v2, v12, v12
	v_fmac_f32_e32 v3, v14, v14
	v_add_f32_e32 v2, v2, v3
	v_add_f32_e32 v1, v1, v2
	v_add_f32_e32 v0, v0, v1
	v_mov_b32_e32 v161, v160
	v_mov_b32_e32 v145, v144
	v_mov_b32_e32 v129, v128
	v_mov_b32_e32 v49, v48
	v_mov_b32_e32 v33, v32
	v_mov_b32_e32 v17, v16
	v_mov_b32_e32 v1, v0
	v_permlane16_swap_b32_e32 v196, v197
	v_permlane16_swap_b32_e32 v160, v161
	v_permlane16_swap_b32_e32 v144, v145
	v_permlane16_swap_b32_e32 v128, v129
	v_permlane16_swap_b32_e32 v48, v49
	v_permlane16_swap_b32_e32 v32, v33
	v_permlane16_swap_b32_e32 v16, v17
	v_permlane16_swap_b32_e32 v0, v1
	v_add_f32_e32 v196, v196, v197
	v_add_f32_e32 v160, v160, v161
	v_add_f32_e32 v144, v144, v145
	v_add_f32_e32 v128, v128, v129
	v_add_f32_e32 v48, v48, v49
	v_add_f32_e32 v32, v32, v33
	v_add_f32_e32 v16, v16, v17
	v_add_f32_e32 v2, v0, v1
	v_mov_b32_e32 v197, v196
	v_mov_b32_e32 v161, v160
	v_mov_b32_e32 v145, v144
	v_mov_b32_e32 v129, v128
	v_mov_b32_e32 v49, v48
	v_mov_b32_e32 v33, v32
	v_mov_b32_e32 v17, v16
	v_mov_b32_e32 v3, v2
	v_permlane32_swap_b32_e32 v196, v197
	v_permlane32_swap_b32_e32 v160, v161
	v_permlane32_swap_b32_e32 v144, v145
	v_permlane32_swap_b32_e32 v128, v129
	v_permlane32_swap_b32_e32 v48, v49
	v_permlane32_swap_b32_e32 v32, v33
	v_permlane32_swap_b32_e32 v16, v17
	v_permlane32_swap_b32_e32 v2, v3
	v_cmp_lt_i32_e32 vcc, 1, v198
	s_and_saveexec_b64 s[20:21], vcc
	s_xor_b64 s[20:21], exec, s[20:21]
	s_cbranch_execz .LBB0_443
	v_cmp_lt_i32_e32 vcc, 2, v198
	s_and_saveexec_b64 s[22:23], vcc
	s_xor_b64 s[22:23], exec, s[22:23]
	v_add_f32_e32 v4, v128, v129
	s_andn2_saveexec_b64 s[22:23], s[22:23]
	v_add_f32_e32 v4, v144, v145
	s_or_b64 exec, exec, s[22:23]
